# P8 sample-row GEMM K loop: register-staged prefetch 6 K steps ahead (VGPR loads + ds_write into a 2-slot LDS ring, same image), fully unrolled
# speedup vs baseline: 1.0005x; 1.0000x over previous
.LBB0_950:
	s_ashr_i32 s3, s2, 31
	s_lshr_b32 s3, s3, 29
	s_add_i32 s3, s2, s3
	s_lshl_b32 s6, s3, 4
	s_and_b32 s3, s3, -8
	s_sub_i32 s16, s2, s3
	s_lshl_b32 s20, s16, 10
	s_ashr_i32 s21, s20, 31
	s_and_b32 s18, s6, 0xffffff80
	s_lshl_b64 s[22:23], s[20:21], 1
	s_add_u32 s20, s0, s22
	s_addc_u32 s21, s1, s23
	s_ashr_i32 s19, s18, 31
	s_lshl_b64 s[36:37], s[18:19], 14
	s_add_u32 s3, s82, s36
	s_addc_u32 s6, s83, s37
	s_add_u32 s22, s3, s22
	s_addc_u32 s23, s6, s23
	v_readfirstlane_b32 s6, v0
	s_lshl_b32 s3, s6, 4
	s_and_b32 s3, s3, 0xfffffc00
	s_add_i32 s3, s3, 0
	s_lshr_b32 s51, s3, 10
	s_and_b32 s52, s51, 3
	s_lshr_b32 s53, s51, 2
	v_and_b32_e32 v179, 63, v0
	v_lshl_add_u32 v176, v179, 4, s3
	s_lshl_b32 s53, s53, 13
	v_add_u32_e32 v177, s53, v1
	s_lshl_b32 s52, s52, 12
	s_add_i32 s52, s52, 0x4000
	v_add_u32_e32 v178, s52, v42
	v_mov_b32_e32 v2, 0
	v_mov_b32_e32 v3, 0
	v_mov_b32_e32 v4, 0
	v_mov_b32_e32 v5, 0
	v_mov_b32_e32 v6, 0
	v_mov_b32_e32 v7, 0
	v_mov_b32_e32 v8, 0
	v_mov_b32_e32 v9, 0
	v_mov_b32_e32 v10, 0
	v_mov_b32_e32 v11, 0
	v_mov_b32_e32 v12, 0
	v_mov_b32_e32 v13, 0
	v_mov_b32_e32 v14, 0
	v_mov_b32_e32 v15, 0
	v_mov_b32_e32 v16, 0
	v_mov_b32_e32 v17, 0
	v_mov_b32_e32 v18, 0
	v_mov_b32_e32 v19, 0
	v_mov_b32_e32 v20, 0
	v_mov_b32_e32 v21, 0
	v_mov_b32_e32 v22, 0
	v_mov_b32_e32 v23, 0
	v_mov_b32_e32 v24, 0
	v_mov_b32_e32 v25, 0
	v_mov_b32_e32 v26, 0
	v_mov_b32_e32 v27, 0
	v_mov_b32_e32 v28, 0
	v_mov_b32_e32 v29, 0
	v_mov_b32_e32 v30, 0
	v_mov_b32_e32 v31, 0
	v_mov_b32_e32 v32, 0
	v_mov_b32_e32 v33, 0
	s_add_u32 s60, s20, 0x0
	s_addc_u32 s61, s21, 0
	s_add_u32 s62, s22, 0x0
	s_addc_u32 s63, s23, 0
	global_load_dwordx4 v[44:47], v184, s[60:61]
	global_load_dwordx4 v[48:51], v184, s[62:63]
	global_load_dwordx4 v[52:55], v186, s[60:61]
	global_load_dwordx4 v[56:59], v186, s[62:63]
	s_add_u32 s60, s20, 0x80
	s_addc_u32 s61, s21, 0
	s_add_u32 s62, s22, 0x80
	s_addc_u32 s63, s23, 0
	global_load_dwordx4 v[60:63], v184, s[60:61]
	global_load_dwordx4 v[64:67], v184, s[62:63]
	global_load_dwordx4 v[68:71], v186, s[60:61]
	global_load_dwordx4 v[72:75], v186, s[62:63]
	s_add_u32 s60, s20, 0x100
	s_addc_u32 s61, s21, 0
	s_add_u32 s62, s22, 0x100
	s_addc_u32 s63, s23, 0
	global_load_dwordx4 v[76:79], v184, s[60:61]
	global_load_dwordx4 v[80:83], v184, s[62:63]
	global_load_dwordx4 v[84:87], v186, s[60:61]
	global_load_dwordx4 v[88:91], v186, s[62:63]
	s_add_u32 s60, s20, 0x180
	s_addc_u32 s61, s21, 0
	s_add_u32 s62, s22, 0x180
	s_addc_u32 s63, s23, 0
	global_load_dwordx4 v[92:95], v184, s[60:61]
	global_load_dwordx4 v[96:99], v184, s[62:63]
	global_load_dwordx4 v[100:103], v186, s[60:61]
	global_load_dwordx4 v[104:107], v186, s[62:63]
	s_add_u32 s60, s20, 0x200
	s_addc_u32 s61, s21, 0
	s_add_u32 s62, s22, 0x200
	s_addc_u32 s63, s23, 0
	global_load_dwordx4 v[136:139], v184, s[60:61]
	global_load_dwordx4 v[140:143], v184, s[62:63]
	global_load_dwordx4 v[144:147], v186, s[60:61]
	global_load_dwordx4 v[148:151], v186, s[62:63]
	s_add_u32 s60, s20, 0x280
	s_addc_u32 s61, s21, 0
	s_add_u32 s62, s22, 0x280
	s_addc_u32 s63, s23, 0
	global_load_dwordx4 v[152:155], v184, s[60:61]
	global_load_dwordx4 v[156:159], v184, s[62:63]
	global_load_dwordx4 v[160:163], v186, s[60:61]
	global_load_dwordx4 v[164:167], v186, s[62:63]
	s_waitcnt vmcnt(20)
	ds_write_b128 v176, v[44:47] offset:0
	ds_write_b128 v176, v[48:51] offset:16384
	ds_write_b128 v176, v[52:55] offset:8192
	ds_write_b128 v176, v[56:59] offset:24576
	s_add_u32 s60, s20, 0x300
	s_addc_u32 s61, s21, 0
	s_add_u32 s62, s22, 0x300
	s_addc_u32 s63, s23, 0
	global_load_dwordx4 v[44:47], v184, s[60:61]
	global_load_dwordx4 v[48:51], v184, s[62:63]
	global_load_dwordx4 v[52:55], v186, s[60:61]
	global_load_dwordx4 v[56:59], v186, s[62:63]
	s_waitcnt lgkmcnt(0)
	s_barrier
	ds_read_b128 v[224:227], v178 offset:0
	ds_read_b128 v[228:231], v178 offset:1024
	ds_read_b128 v[232:235], v178 offset:2048
	ds_read_b128 v[236:239], v178 offset:3072
	ds_read_b128 v[188:191], v177 offset:0
	ds_read_b128 v[192:195], v177 offset:1024
	ds_read_b128 v[196:199], v177 offset:2048
	ds_read_b128 v[200:203], v177 offset:3072
	ds_read_b128 v[204:207], v177 offset:4096
	ds_read_b128 v[212:215], v177 offset:5120
	ds_read_b128 v[216:219], v177 offset:6144
	ds_read_b128 v[220:223], v177 offset:7168
	s_waitcnt lgkmcnt(0)
	v_mfma_f32_16x16x32_bf16 v[30:33], v[224:227], v[188:191], v[30:33]
	v_mfma_f32_16x16x32_bf16 v[26:29], v[232:235], v[188:191], v[26:29]
	v_mfma_f32_16x16x32_bf16 v[22:25], v[224:227], v[196:199], v[22:25]
	v_mfma_f32_16x16x32_bf16 v[14:17], v[232:235], v[196:199], v[14:17]
	v_mfma_f32_16x16x32_bf16 v[10:13], v[224:227], v[204:207], v[10:13]
	v_mfma_f32_16x16x32_bf16 v[6:9], v[232:235], v[204:207], v[6:9]
	v_mfma_f32_16x16x32_bf16 v[2:5], v[224:227], v[216:219], v[2:5]
	v_mfma_f32_16x16x32_bf16 v[18:21], v[232:235], v[216:219], v[18:21]
	v_mfma_f32_16x16x32_bf16 v[30:33], v[228:231], v[192:195], v[30:33]
	v_mfma_f32_16x16x32_bf16 v[26:29], v[236:239], v[192:195], v[26:29]
	v_mfma_f32_16x16x32_bf16 v[22:25], v[228:231], v[200:203], v[22:25]
	v_mfma_f32_16x16x32_bf16 v[14:17], v[236:239], v[200:203], v[14:17]
	v_mfma_f32_16x16x32_bf16 v[10:13], v[228:231], v[212:215], v[10:13]
	v_mfma_f32_16x16x32_bf16 v[6:9], v[236:239], v[212:215], v[6:9]
	v_mfma_f32_16x16x32_bf16 v[2:5], v[228:231], v[220:223], v[2:5]
	v_mfma_f32_16x16x32_bf16 v[18:21], v[236:239], v[220:223], v[18:21]
	s_waitcnt vmcnt(20)
	ds_write_b128 v176, v[60:63] offset:32768
	ds_write_b128 v176, v[64:67] offset:49152
	ds_write_b128 v176, v[68:71] offset:40960
	ds_write_b128 v176, v[72:75] offset:57344
	s_add_u32 s60, s20, 0x380
	s_addc_u32 s61, s21, 0
	s_add_u32 s62, s22, 0x380
	s_addc_u32 s63, s23, 0
	global_load_dwordx4 v[60:63], v184, s[60:61]
	global_load_dwordx4 v[64:67], v184, s[62:63]
	global_load_dwordx4 v[68:71], v186, s[60:61]
	global_load_dwordx4 v[72:75], v186, s[62:63]
	s_waitcnt lgkmcnt(0)
	s_barrier
	ds_read_b128 v[224:227], v178 offset:32768
	ds_read_b128 v[228:231], v178 offset:33792
	ds_read_b128 v[232:235], v178 offset:34816
	ds_read_b128 v[236:239], v178 offset:35840
	ds_read_b128 v[188:191], v177 offset:32768
	ds_read_b128 v[192:195], v177 offset:33792
	ds_read_b128 v[196:199], v177 offset:34816
	ds_read_b128 v[200:203], v177 offset:35840
	ds_read_b128 v[204:207], v177 offset:36864
	ds_read_b128 v[212:215], v177 offset:37888
	ds_read_b128 v[216:219], v177 offset:38912
	ds_read_b128 v[220:223], v177 offset:39936
	s_waitcnt lgkmcnt(0)
	v_mfma_f32_16x16x32_bf16 v[30:33], v[224:227], v[188:191], v[30:33]
	v_mfma_f32_16x16x32_bf16 v[26:29], v[232:235], v[188:191], v[26:29]
	v_mfma_f32_16x16x32_bf16 v[22:25], v[224:227], v[196:199], v[22:25]
	v_mfma_f32_16x16x32_bf16 v[14:17], v[232:235], v[196:199], v[14:17]
	v_mfma_f32_16x16x32_bf16 v[10:13], v[224:227], v[204:207], v[10:13]
	v_mfma_f32_16x16x32_bf16 v[6:9], v[232:235], v[204:207], v[6:9]
	v_mfma_f32_16x16x32_bf16 v[2:5], v[224:227], v[216:219], v[2:5]
	v_mfma_f32_16x16x32_bf16 v[18:21], v[232:235], v[216:219], v[18:21]
	v_mfma_f32_16x16x32_bf16 v[30:33], v[228:231], v[192:195], v[30:33]
	v_mfma_f32_16x16x32_bf16 v[26:29], v[236:239], v[192:195], v[26:29]
	v_mfma_f32_16x16x32_bf16 v[22:25], v[228:231], v[200:203], v[22:25]
	v_mfma_f32_16x16x32_bf16 v[14:17], v[236:239], v[200:203], v[14:17]
	v_mfma_f32_16x16x32_bf16 v[10:13], v[228:231], v[212:215], v[10:13]
	v_mfma_f32_16x16x32_bf16 v[6:9], v[236:239], v[212:215], v[6:9]
	v_mfma_f32_16x16x32_bf16 v[2:5], v[228:231], v[220:223], v[2:5]
	v_mfma_f32_16x16x32_bf16 v[18:21], v[236:239], v[220:223], v[18:21]
	s_waitcnt vmcnt(20)
	ds_write_b128 v176, v[76:79] offset:0
	ds_write_b128 v176, v[80:83] offset:16384
	ds_write_b128 v176, v[84:87] offset:8192
	ds_write_b128 v176, v[88:91] offset:24576
	s_add_u32 s60, s20, 0x400
	s_addc_u32 s61, s21, 0
	s_add_u32 s62, s22, 0x400
	s_addc_u32 s63, s23, 0
	global_load_dwordx4 v[76:79], v184, s[60:61]
	global_load_dwordx4 v[80:83], v184, s[62:63]
	global_load_dwordx4 v[84:87], v186, s[60:61]
	global_load_dwordx4 v[88:91], v186, s[62:63]
	s_waitcnt lgkmcnt(0)
	s_barrier
	ds_read_b128 v[224:227], v178 offset:0
	ds_read_b128 v[228:231], v178 offset:1024
	ds_read_b128 v[232:235], v178 offset:2048
	ds_read_b128 v[236:239], v178 offset:3072
	ds_read_b128 v[188:191], v177 offset:0
	ds_read_b128 v[192:195], v177 offset:1024
	ds_read_b128 v[196:199], v177 offset:2048
	ds_read_b128 v[200:203], v177 offset:3072
	ds_read_b128 v[204:207], v177 offset:4096
	ds_read_b128 v[212:215], v177 offset:5120
	ds_read_b128 v[216:219], v177 offset:6144
	ds_read_b128 v[220:223], v177 offset:7168
	s_waitcnt lgkmcnt(0)
	v_mfma_f32_16x16x32_bf16 v[30:33], v[224:227], v[188:191], v[30:33]
	v_mfma_f32_16x16x32_bf16 v[26:29], v[232:235], v[188:191], v[26:29]
	v_mfma_f32_16x16x32_bf16 v[22:25], v[224:227], v[196:199], v[22:25]
	v_mfma_f32_16x16x32_bf16 v[14:17], v[232:235], v[196:199], v[14:17]
	v_mfma_f32_16x16x32_bf16 v[10:13], v[224:227], v[204:207], v[10:13]
	v_mfma_f32_16x16x32_bf16 v[6:9], v[232:235], v[204:207], v[6:9]
	v_mfma_f32_16x16x32_bf16 v[2:5], v[224:227], v[216:219], v[2:5]
	v_mfma_f32_16x16x32_bf16 v[18:21], v[232:235], v[216:219], v[18:21]
	v_mfma_f32_16x16x32_bf16 v[30:33], v[228:231], v[192:195], v[30:33]
	v_mfma_f32_16x16x32_bf16 v[26:29], v[236:239], v[192:195], v[26:29]
	v_mfma_f32_16x16x32_bf16 v[22:25], v[228:231], v[200:203], v[22:25]
	v_mfma_f32_16x16x32_bf16 v[14:17], v[236:239], v[200:203], v[14:17]
	v_mfma_f32_16x16x32_bf16 v[10:13], v[228:231], v[212:215], v[10:13]
	v_mfma_f32_16x16x32_bf16 v[6:9], v[236:239], v[212:215], v[6:9]
	v_mfma_f32_16x16x32_bf16 v[2:5], v[228:231], v[220:223], v[2:5]
	v_mfma_f32_16x16x32_bf16 v[18:21], v[236:239], v[220:223], v[18:21]
	s_waitcnt vmcnt(20)
	ds_write_b128 v176, v[92:95] offset:32768
	ds_write_b128 v176, v[96:99] offset:49152
	ds_write_b128 v176, v[100:103] offset:40960
	ds_write_b128 v176, v[104:107] offset:57344
	s_add_u32 s60, s20, 0x480
	s_addc_u32 s61, s21, 0
	s_add_u32 s62, s22, 0x480
	s_addc_u32 s63, s23, 0
	global_load_dwordx4 v[92:95], v184, s[60:61]
	global_load_dwordx4 v[96:99], v184, s[62:63]
	global_load_dwordx4 v[100:103], v186, s[60:61]
	global_load_dwordx4 v[104:107], v186, s[62:63]
	s_waitcnt lgkmcnt(0)
	s_barrier
	ds_read_b128 v[224:227], v178 offset:32768
	ds_read_b128 v[228:231], v178 offset:33792
	ds_read_b128 v[232:235], v178 offset:34816
	ds_read_b128 v[236:239], v178 offset:35840
	ds_read_b128 v[188:191], v177 offset:32768
	ds_read_b128 v[192:195], v177 offset:33792
	ds_read_b128 v[196:199], v177 offset:34816
	ds_read_b128 v[200:203], v177 offset:35840
	ds_read_b128 v[204:207], v177 offset:36864
	ds_read_b128 v[212:215], v177 offset:37888
	ds_read_b128 v[216:219], v177 offset:38912
	ds_read_b128 v[220:223], v177 offset:39936
	s_waitcnt lgkmcnt(0)
	v_mfma_f32_16x16x32_bf16 v[30:33], v[224:227], v[188:191], v[30:33]
	v_mfma_f32_16x16x32_bf16 v[26:29], v[232:235], v[188:191], v[26:29]
	v_mfma_f32_16x16x32_bf16 v[22:25], v[224:227], v[196:199], v[22:25]
	v_mfma_f32_16x16x32_bf16 v[14:17], v[232:235], v[196:199], v[14:17]
	v_mfma_f32_16x16x32_bf16 v[10:13], v[224:227], v[204:207], v[10:13]
	v_mfma_f32_16x16x32_bf16 v[6:9], v[232:235], v[204:207], v[6:9]
	v_mfma_f32_16x16x32_bf16 v[2:5], v[224:227], v[216:219], v[2:5]
	v_mfma_f32_16x16x32_bf16 v[18:21], v[232:235], v[216:219], v[18:21]
	v_mfma_f32_16x16x32_bf16 v[30:33], v[228:231], v[192:195], v[30:33]
	v_mfma_f32_16x16x32_bf16 v[26:29], v[236:239], v[192:195], v[26:29]
	v_mfma_f32_16x16x32_bf16 v[22:25], v[228:231], v[200:203], v[22:25]
	v_mfma_f32_16x16x32_bf16 v[14:17], v[236:239], v[200:203], v[14:17]
	v_mfma_f32_16x16x32_bf16 v[10:13], v[228:231], v[212:215], v[10:13]
	v_mfma_f32_16x16x32_bf16 v[6:9], v[236:239], v[212:215], v[6:9]
	v_mfma_f32_16x16x32_bf16 v[2:5], v[228:231], v[220:223], v[2:5]
	v_mfma_f32_16x16x32_bf16 v[18:21], v[236:239], v[220:223], v[18:21]
	s_waitcnt vmcnt(20)
	ds_write_b128 v176, v[136:139] offset:0
	ds_write_b128 v176, v[140:143] offset:16384
	ds_write_b128 v176, v[144:147] offset:8192
	ds_write_b128 v176, v[148:151] offset:24576
	s_add_u32 s60, s20, 0x500
	s_addc_u32 s61, s21, 0
	s_add_u32 s62, s22, 0x500
	s_addc_u32 s63, s23, 0
	global_load_dwordx4 v[136:139], v184, s[60:61]
	global_load_dwordx4 v[140:143], v184, s[62:63]
	global_load_dwordx4 v[144:147], v186, s[60:61]
	global_load_dwordx4 v[148:151], v186, s[62:63]
	s_waitcnt lgkmcnt(0)
	s_barrier
	ds_read_b128 v[224:227], v178 offset:0
	ds_read_b128 v[228:231], v178 offset:1024
	ds_read_b128 v[232:235], v178 offset:2048
	ds_read_b128 v[236:239], v178 offset:3072
	ds_read_b128 v[188:191], v177 offset:0
	ds_read_b128 v[192:195], v177 offset:1024
	ds_read_b128 v[196:199], v177 offset:2048
	ds_read_b128 v[200:203], v177 offset:3072
	ds_read_b128 v[204:207], v177 offset:4096
	ds_read_b128 v[212:215], v177 offset:5120
	ds_read_b128 v[216:219], v177 offset:6144
	ds_read_b128 v[220:223], v177 offset:7168
	s_waitcnt lgkmcnt(0)
	v_mfma_f32_16x16x32_bf16 v[30:33], v[224:227], v[188:191], v[30:33]
	v_mfma_f32_16x16x32_bf16 v[26:29], v[232:235], v[188:191], v[26:29]
	v_mfma_f32_16x16x32_bf16 v[22:25], v[224:227], v[196:199], v[22:25]
	v_mfma_f32_16x16x32_bf16 v[14:17], v[232:235], v[196:199], v[14:17]
	v_mfma_f32_16x16x32_bf16 v[10:13], v[224:227], v[204:207], v[10:13]
	v_mfma_f32_16x16x32_bf16 v[6:9], v[232:235], v[204:207], v[6:9]
	v_mfma_f32_16x16x32_bf16 v[2:5], v[224:227], v[216:219], v[2:5]
	v_mfma_f32_16x16x32_bf16 v[18:21], v[232:235], v[216:219], v[18:21]
	v_mfma_f32_16x16x32_bf16 v[30:33], v[228:231], v[192:195], v[30:33]
	v_mfma_f32_16x16x32_bf16 v[26:29], v[236:239], v[192:195], v[26:29]
	v_mfma_f32_16x16x32_bf16 v[22:25], v[228:231], v[200:203], v[22:25]
	v_mfma_f32_16x16x32_bf16 v[14:17], v[236:239], v[200:203], v[14:17]
	v_mfma_f32_16x16x32_bf16 v[10:13], v[228:231], v[212:215], v[10:13]
	v_mfma_f32_16x16x32_bf16 v[6:9], v[236:239], v[212:215], v[6:9]
	v_mfma_f32_16x16x32_bf16 v[2:5], v[228:231], v[220:223], v[2:5]
	v_mfma_f32_16x16x32_bf16 v[18:21], v[236:239], v[220:223], v[18:21]
	s_waitcnt vmcnt(20)
	ds_write_b128 v176, v[152:155] offset:32768
	ds_write_b128 v176, v[156:159] offset:49152
	ds_write_b128 v176, v[160:163] offset:40960
	ds_write_b128 v176, v[164:167] offset:57344
	s_add_u32 s60, s20, 0x580
	s_addc_u32 s61, s21, 0
	s_add_u32 s62, s22, 0x580
	s_addc_u32 s63, s23, 0
	global_load_dwordx4 v[152:155], v184, s[60:61]
	global_load_dwordx4 v[156:159], v184, s[62:63]
	global_load_dwordx4 v[160:163], v186, s[60:61]
	global_load_dwordx4 v[164:167], v186, s[62:63]
	s_waitcnt lgkmcnt(0)
	s_barrier
	ds_read_b128 v[224:227], v178 offset:32768
	ds_read_b128 v[228:231], v178 offset:33792
	ds_read_b128 v[232:235], v178 offset:34816
	ds_read_b128 v[236:239], v178 offset:35840
	ds_read_b128 v[188:191], v177 offset:32768
	ds_read_b128 v[192:195], v177 offset:33792
	ds_read_b128 v[196:199], v177 offset:34816
	ds_read_b128 v[200:203], v177 offset:35840
	ds_read_b128 v[204:207], v177 offset:36864
	ds_read_b128 v[212:215], v177 offset:37888
	ds_read_b128 v[216:219], v177 offset:38912
	ds_read_b128 v[220:223], v177 offset:39936
	s_waitcnt lgkmcnt(0)
	v_mfma_f32_16x16x32_bf16 v[30:33], v[224:227], v[188:191], v[30:33]
	v_mfma_f32_16x16x32_bf16 v[26:29], v[232:235], v[188:191], v[26:29]
	v_mfma_f32_16x16x32_bf16 v[22:25], v[224:227], v[196:199], v[22:25]
	v_mfma_f32_16x16x32_bf16 v[14:17], v[232:235], v[196:199], v[14:17]
	v_mfma_f32_16x16x32_bf16 v[10:13], v[224:227], v[204:207], v[10:13]
	v_mfma_f32_16x16x32_bf16 v[6:9], v[232:235], v[204:207], v[6:9]
	v_mfma_f32_16x16x32_bf16 v[2:5], v[224:227], v[216:219], v[2:5]
	v_mfma_f32_16x16x32_bf16 v[18:21], v[232:235], v[216:219], v[18:21]
	v_mfma_f32_16x16x32_bf16 v[30:33], v[228:231], v[192:195], v[30:33]
	v_mfma_f32_16x16x32_bf16 v[26:29], v[236:239], v[192:195], v[26:29]
	v_mfma_f32_16x16x32_bf16 v[22:25], v[228:231], v[200:203], v[22:25]
	v_mfma_f32_16x16x32_bf16 v[14:17], v[236:239], v[200:203], v[14:17]
	v_mfma_f32_16x16x32_bf16 v[10:13], v[228:231], v[212:215], v[10:13]
	v_mfma_f32_16x16x32_bf16 v[6:9], v[236:239], v[212:215], v[6:9]
	v_mfma_f32_16x16x32_bf16 v[2:5], v[228:231], v[220:223], v[2:5]
	v_mfma_f32_16x16x32_bf16 v[18:21], v[236:239], v[220:223], v[18:21]
	s_waitcnt vmcnt(20)
	ds_write_b128 v176, v[44:47] offset:0
	ds_write_b128 v176, v[48:51] offset:16384
	ds_write_b128 v176, v[52:55] offset:8192
	ds_write_b128 v176, v[56:59] offset:24576
	s_add_u32 s60, s20, 0x600
	s_addc_u32 s61, s21, 0
	s_add_u32 s62, s22, 0x600
	s_addc_u32 s63, s23, 0
	global_load_dwordx4 v[44:47], v184, s[60:61]
	global_load_dwordx4 v[48:51], v184, s[62:63]
	global_load_dwordx4 v[52:55], v186, s[60:61]
	global_load_dwordx4 v[56:59], v186, s[62:63]
	s_waitcnt lgkmcnt(0)
	s_barrier
	ds_read_b128 v[224:227], v178 offset:0
	ds_read_b128 v[228:231], v178 offset:1024
	ds_read_b128 v[232:235], v178 offset:2048
	ds_read_b128 v[236:239], v178 offset:3072
	ds_read_b128 v[188:191], v177 offset:0
	ds_read_b128 v[192:195], v177 offset:1024
	ds_read_b128 v[196:199], v177 offset:2048
	ds_read_b128 v[200:203], v177 offset:3072
	ds_read_b128 v[204:207], v177 offset:4096
	ds_read_b128 v[212:215], v177 offset:5120
	ds_read_b128 v[216:219], v177 offset:6144
	ds_read_b128 v[220:223], v177 offset:7168
	s_waitcnt lgkmcnt(0)
	v_mfma_f32_16x16x32_bf16 v[30:33], v[224:227], v[188:191], v[30:33]
	v_mfma_f32_16x16x32_bf16 v[26:29], v[232:235], v[188:191], v[26:29]
	v_mfma_f32_16x16x32_bf16 v[22:25], v[224:227], v[196:199], v[22:25]
	v_mfma_f32_16x16x32_bf16 v[14:17], v[232:235], v[196:199], v[14:17]
	v_mfma_f32_16x16x32_bf16 v[10:13], v[224:227], v[204:207], v[10:13]
	v_mfma_f32_16x16x32_bf16 v[6:9], v[232:235], v[204:207], v[6:9]
	v_mfma_f32_16x16x32_bf16 v[2:5], v[224:227], v[216:219], v[2:5]
	v_mfma_f32_16x16x32_bf16 v[18:21], v[232:235], v[216:219], v[18:21]
	v_mfma_f32_16x16x32_bf16 v[30:33], v[228:231], v[192:195], v[30:33]
	v_mfma_f32_16x16x32_bf16 v[26:29], v[236:239], v[192:195], v[26:29]
	v_mfma_f32_16x16x32_bf16 v[22:25], v[228:231], v[200:203], v[22:25]
	v_mfma_f32_16x16x32_bf16 v[14:17], v[236:239], v[200:203], v[14:17]
	v_mfma_f32_16x16x32_bf16 v[10:13], v[228:231], v[212:215], v[10:13]
	v_mfma_f32_16x16x32_bf16 v[6:9], v[236:239], v[212:215], v[6:9]
	v_mfma_f32_16x16x32_bf16 v[2:5], v[228:231], v[220:223], v[2:5]
	v_mfma_f32_16x16x32_bf16 v[18:21], v[236:239], v[220:223], v[18:21]
	s_waitcnt vmcnt(20)
	ds_write_b128 v176, v[60:63] offset:32768
	ds_write_b128 v176, v[64:67] offset:49152
	ds_write_b128 v176, v[68:71] offset:40960
	ds_write_b128 v176, v[72:75] offset:57344
	s_add_u32 s60, s20, 0x680
	s_addc_u32 s61, s21, 0
	s_add_u32 s62, s22, 0x680
	s_addc_u32 s63, s23, 0
	global_load_dwordx4 v[60:63], v184, s[60:61]
	global_load_dwordx4 v[64:67], v184, s[62:63]
	global_load_dwordx4 v[68:71], v186, s[60:61]
	global_load_dwordx4 v[72:75], v186, s[62:63]
	s_waitcnt lgkmcnt(0)
	s_barrier
	ds_read_b128 v[224:227], v178 offset:32768
	ds_read_b128 v[228:231], v178 offset:33792
	ds_read_b128 v[232:235], v178 offset:34816
	ds_read_b128 v[236:239], v178 offset:35840
	ds_read_b128 v[188:191], v177 offset:32768
	ds_read_b128 v[192:195], v177 offset:33792
	ds_read_b128 v[196:199], v177 offset:34816
	ds_read_b128 v[200:203], v177 offset:35840
	ds_read_b128 v[204:207], v177 offset:36864
	ds_read_b128 v[212:215], v177 offset:37888
	ds_read_b128 v[216:219], v177 offset:38912
	ds_read_b128 v[220:223], v177 offset:39936
	s_waitcnt lgkmcnt(0)
	v_mfma_f32_16x16x32_bf16 v[30:33], v[224:227], v[188:191], v[30:33]
	v_mfma_f32_16x16x32_bf16 v[26:29], v[232:235], v[188:191], v[26:29]
	v_mfma_f32_16x16x32_bf16 v[22:25], v[224:227], v[196:199], v[22:25]
	v_mfma_f32_16x16x32_bf16 v[14:17], v[232:235], v[196:199], v[14:17]
	v_mfma_f32_16x16x32_bf16 v[10:13], v[224:227], v[204:207], v[10:13]
	v_mfma_f32_16x16x32_bf16 v[6:9], v[232:235], v[204:207], v[6:9]
	v_mfma_f32_16x16x32_bf16 v[2:5], v[224:227], v[216:219], v[2:5]
	v_mfma_f32_16x16x32_bf16 v[18:21], v[232:235], v[216:219], v[18:21]
	v_mfma_f32_16x16x32_bf16 v[30:33], v[228:231], v[192:195], v[30:33]
	v_mfma_f32_16x16x32_bf16 v[26:29], v[236:239], v[192:195], v[26:29]
	v_mfma_f32_16x16x32_bf16 v[22:25], v[228:231], v[200:203], v[22:25]
	v_mfma_f32_16x16x32_bf16 v[14:17], v[236:239], v[200:203], v[14:17]
	v_mfma_f32_16x16x32_bf16 v[10:13], v[228:231], v[212:215], v[10:13]
	v_mfma_f32_16x16x32_bf16 v[6:9], v[236:239], v[212:215], v[6:9]
	v_mfma_f32_16x16x32_bf16 v[2:5], v[228:231], v[220:223], v[2:5]
	v_mfma_f32_16x16x32_bf16 v[18:21], v[236:239], v[220:223], v[18:21]
	s_waitcnt vmcnt(20)
	ds_write_b128 v176, v[76:79] offset:0
	ds_write_b128 v176, v[80:83] offset:16384
	ds_write_b128 v176, v[84:87] offset:8192
	ds_write_b128 v176, v[88:91] offset:24576
	s_add_u32 s60, s20, 0x700
	s_addc_u32 s61, s21, 0
	s_add_u32 s62, s22, 0x700
	s_addc_u32 s63, s23, 0
	global_load_dwordx4 v[76:79], v184, s[60:61]
	global_load_dwordx4 v[80:83], v184, s[62:63]
	global_load_dwordx4 v[84:87], v186, s[60:61]
	global_load_dwordx4 v[88:91], v186, s[62:63]
	s_waitcnt lgkmcnt(0)
	s_barrier
	ds_read_b128 v[224:227], v178 offset:0
	ds_read_b128 v[228:231], v178 offset:1024
	ds_read_b128 v[232:235], v178 offset:2048
	ds_read_b128 v[236:239], v178 offset:3072
	ds_read_b128 v[188:191], v177 offset:0
	ds_read_b128 v[192:195], v177 offset:1024
	ds_read_b128 v[196:199], v177 offset:2048
	ds_read_b128 v[200:203], v177 offset:3072
	ds_read_b128 v[204:207], v177 offset:4096
	ds_read_b128 v[212:215], v177 offset:5120
	ds_read_b128 v[216:219], v177 offset:6144
	ds_read_b128 v[220:223], v177 offset:7168
	s_waitcnt lgkmcnt(0)
	v_mfma_f32_16x16x32_bf16 v[30:33], v[224:227], v[188:191], v[30:33]
	v_mfma_f32_16x16x32_bf16 v[26:29], v[232:235], v[188:191], v[26:29]
	v_mfma_f32_16x16x32_bf16 v[22:25], v[224:227], v[196:199], v[22:25]
	v_mfma_f32_16x16x32_bf16 v[14:17], v[232:235], v[196:199], v[14:17]
	v_mfma_f32_16x16x32_bf16 v[10:13], v[224:227], v[204:207], v[10:13]
	v_mfma_f32_16x16x32_bf16 v[6:9], v[232:235], v[204:207], v[6:9]
	v_mfma_f32_16x16x32_bf16 v[2:5], v[224:227], v[216:219], v[2:5]
	v_mfma_f32_16x16x32_bf16 v[18:21], v[232:235], v[216:219], v[18:21]
	v_mfma_f32_16x16x32_bf16 v[30:33], v[228:231], v[192:195], v[30:33]
	v_mfma_f32_16x16x32_bf16 v[26:29], v[236:239], v[192:195], v[26:29]
	v_mfma_f32_16x16x32_bf16 v[22:25], v[228:231], v[200:203], v[22:25]
	v_mfma_f32_16x16x32_bf16 v[14:17], v[236:239], v[200:203], v[14:17]
	v_mfma_f32_16x16x32_bf16 v[10:13], v[228:231], v[212:215], v[10:13]
	v_mfma_f32_16x16x32_bf16 v[6:9], v[236:239], v[212:215], v[6:9]
	v_mfma_f32_16x16x32_bf16 v[2:5], v[228:231], v[220:223], v[2:5]
	v_mfma_f32_16x16x32_bf16 v[18:21], v[236:239], v[220:223], v[18:21]
	s_waitcnt vmcnt(20)
	ds_write_b128 v176, v[92:95] offset:32768
	ds_write_b128 v176, v[96:99] offset:49152
	ds_write_b128 v176, v[100:103] offset:40960
	ds_write_b128 v176, v[104:107] offset:57344
	s_add_u32 s60, s20, 0x780
	s_addc_u32 s61, s21, 0
	s_add_u32 s62, s22, 0x780
	s_addc_u32 s63, s23, 0
	global_load_dwordx4 v[92:95], v184, s[60:61]
	global_load_dwordx4 v[96:99], v184, s[62:63]
	global_load_dwordx4 v[100:103], v186, s[60:61]
	global_load_dwordx4 v[104:107], v186, s[62:63]
	s_waitcnt lgkmcnt(0)
	s_barrier
	ds_read_b128 v[224:227], v178 offset:32768
	ds_read_b128 v[228:231], v178 offset:33792
	ds_read_b128 v[232:235], v178 offset:34816
	ds_read_b128 v[236:239], v178 offset:35840
	ds_read_b128 v[188:191], v177 offset:32768
	ds_read_b128 v[192:195], v177 offset:33792
	ds_read_b128 v[196:199], v177 offset:34816
	ds_read_b128 v[200:203], v177 offset:35840
	ds_read_b128 v[204:207], v177 offset:36864
	ds_read_b128 v[212:215], v177 offset:37888
	ds_read_b128 v[216:219], v177 offset:38912
	ds_read_b128 v[220:223], v177 offset:39936
	s_waitcnt lgkmcnt(0)
	v_mfma_f32_16x16x32_bf16 v[30:33], v[224:227], v[188:191], v[30:33]
	v_mfma_f32_16x16x32_bf16 v[26:29], v[232:235], v[188:191], v[26:29]
	v_mfma_f32_16x16x32_bf16 v[22:25], v[224:227], v[196:199], v[22:25]
	v_mfma_f32_16x16x32_bf16 v[14:17], v[232:235], v[196:199], v[14:17]
	v_mfma_f32_16x16x32_bf16 v[10:13], v[224:227], v[204:207], v[10:13]
	v_mfma_f32_16x16x32_bf16 v[6:9], v[232:235], v[204:207], v[6:9]
	v_mfma_f32_16x16x32_bf16 v[2:5], v[224:227], v[216:219], v[2:5]
	v_mfma_f32_16x16x32_bf16 v[18:21], v[232:235], v[216:219], v[18:21]
	v_mfma_f32_16x16x32_bf16 v[30:33], v[228:231], v[192:195], v[30:33]
	v_mfma_f32_16x16x32_bf16 v[26:29], v[236:239], v[192:195], v[26:29]
	v_mfma_f32_16x16x32_bf16 v[22:25], v[228:231], v[200:203], v[22:25]
	v_mfma_f32_16x16x32_bf16 v[14:17], v[236:239], v[200:203], v[14:17]
	v_mfma_f32_16x16x32_bf16 v[10:13], v[228:231], v[212:215], v[10:13]
	v_mfma_f32_16x16x32_bf16 v[6:9], v[236:239], v[212:215], v[6:9]
	v_mfma_f32_16x16x32_bf16 v[2:5], v[228:231], v[220:223], v[2:5]
	v_mfma_f32_16x16x32_bf16 v[18:21], v[236:239], v[220:223], v[18:21]
	s_waitcnt vmcnt(20)
	ds_write_b128 v176, v[136:139] offset:0
	ds_write_b128 v176, v[140:143] offset:16384
	ds_write_b128 v176, v[144:147] offset:8192
	ds_write_b128 v176, v[148:151] offset:24576
	s_waitcnt lgkmcnt(0)
	s_barrier
	ds_read_b128 v[224:227], v178 offset:0
	ds_read_b128 v[228:231], v178 offset:1024
	ds_read_b128 v[232:235], v178 offset:2048
	ds_read_b128 v[236:239], v178 offset:3072
	ds_read_b128 v[188:191], v177 offset:0
	ds_read_b128 v[192:195], v177 offset:1024
	ds_read_b128 v[196:199], v177 offset:2048
	ds_read_b128 v[200:203], v177 offset:3072
	ds_read_b128 v[204:207], v177 offset:4096
	ds_read_b128 v[212:215], v177 offset:5120
	ds_read_b128 v[216:219], v177 offset:6144
	ds_read_b128 v[220:223], v177 offset:7168
	s_waitcnt lgkmcnt(0)
	v_mfma_f32_16x16x32_bf16 v[30:33], v[224:227], v[188:191], v[30:33]
	v_mfma_f32_16x16x32_bf16 v[26:29], v[232:235], v[188:191], v[26:29]
	v_mfma_f32_16x16x32_bf16 v[22:25], v[224:227], v[196:199], v[22:25]
	v_mfma_f32_16x16x32_bf16 v[14:17], v[232:235], v[196:199], v[14:17]
	v_mfma_f32_16x16x32_bf16 v[10:13], v[224:227], v[204:207], v[10:13]
	v_mfma_f32_16x16x32_bf16 v[6:9], v[232:235], v[204:207], v[6:9]
	v_mfma_f32_16x16x32_bf16 v[2:5], v[224:227], v[216:219], v[2:5]
	v_mfma_f32_16x16x32_bf16 v[18:21], v[232:235], v[216:219], v[18:21]
	v_mfma_f32_16x16x32_bf16 v[30:33], v[228:231], v[192:195], v[30:33]
	v_mfma_f32_16x16x32_bf16 v[26:29], v[236:239], v[192:195], v[26:29]
	v_mfma_f32_16x16x32_bf16 v[22:25], v[228:231], v[200:203], v[22:25]
	v_mfma_f32_16x16x32_bf16 v[14:17], v[236:239], v[200:203], v[14:17]
	v_mfma_f32_16x16x32_bf16 v[10:13], v[228:231], v[212:215], v[10:13]
	v_mfma_f32_16x16x32_bf16 v[6:9], v[236:239], v[212:215], v[6:9]
	v_mfma_f32_16x16x32_bf16 v[2:5], v[228:231], v[220:223], v[2:5]
	v_mfma_f32_16x16x32_bf16 v[18:21], v[236:239], v[220:223], v[18:21]
	s_waitcnt vmcnt(16)
	ds_write_b128 v176, v[152:155] offset:32768
	ds_write_b128 v176, v[156:159] offset:49152
	ds_write_b128 v176, v[160:163] offset:40960
	ds_write_b128 v176, v[164:167] offset:57344
	s_waitcnt lgkmcnt(0)
	s_barrier
	ds_read_b128 v[224:227], v178 offset:32768
	ds_read_b128 v[228:231], v178 offset:33792
	ds_read_b128 v[232:235], v178 offset:34816
	ds_read_b128 v[236:239], v178 offset:35840
	ds_read_b128 v[188:191], v177 offset:32768
	ds_read_b128 v[192:195], v177 offset:33792
	ds_read_b128 v[196:199], v177 offset:34816
	ds_read_b128 v[200:203], v177 offset:35840
	ds_read_b128 v[204:207], v177 offset:36864
	ds_read_b128 v[212:215], v177 offset:37888
	ds_read_b128 v[216:219], v177 offset:38912
	ds_read_b128 v[220:223], v177 offset:39936
	s_waitcnt lgkmcnt(0)
	v_mfma_f32_16x16x32_bf16 v[30:33], v[224:227], v[188:191], v[30:33]
	v_mfma_f32_16x16x32_bf16 v[26:29], v[232:235], v[188:191], v[26:29]
	v_mfma_f32_16x16x32_bf16 v[22:25], v[224:227], v[196:199], v[22:25]
	v_mfma_f32_16x16x32_bf16 v[14:17], v[232:235], v[196:199], v[14:17]
	v_mfma_f32_16x16x32_bf16 v[10:13], v[224:227], v[204:207], v[10:13]
	v_mfma_f32_16x16x32_bf16 v[6:9], v[232:235], v[204:207], v[6:9]
	v_mfma_f32_16x16x32_bf16 v[2:5], v[224:227], v[216:219], v[2:5]
	v_mfma_f32_16x16x32_bf16 v[18:21], v[232:235], v[216:219], v[18:21]
	v_mfma_f32_16x16x32_bf16 v[30:33], v[228:231], v[192:195], v[30:33]
	v_mfma_f32_16x16x32_bf16 v[26:29], v[236:239], v[192:195], v[26:29]
	v_mfma_f32_16x16x32_bf16 v[22:25], v[228:231], v[200:203], v[22:25]
	v_mfma_f32_16x16x32_bf16 v[14:17], v[236:239], v[200:203], v[14:17]
	v_mfma_f32_16x16x32_bf16 v[10:13], v[228:231], v[212:215], v[10:13]
	v_mfma_f32_16x16x32_bf16 v[6:9], v[236:239], v[212:215], v[6:9]
	v_mfma_f32_16x16x32_bf16 v[2:5], v[228:231], v[220:223], v[2:5]
	v_mfma_f32_16x16x32_bf16 v[18:21], v[236:239], v[220:223], v[18:21]
	s_waitcnt vmcnt(12)
	ds_write_b128 v176, v[44:47] offset:0
	ds_write_b128 v176, v[48:51] offset:16384
	ds_write_b128 v176, v[52:55] offset:8192
	ds_write_b128 v176, v[56:59] offset:24576
	s_waitcnt lgkmcnt(0)
	s_barrier
	ds_read_b128 v[224:227], v178 offset:0
	ds_read_b128 v[228:231], v178 offset:1024
	ds_read_b128 v[232:235], v178 offset:2048
	ds_read_b128 v[236:239], v178 offset:3072
	ds_read_b128 v[188:191], v177 offset:0
	ds_read_b128 v[192:195], v177 offset:1024
	ds_read_b128 v[196:199], v177 offset:2048
	ds_read_b128 v[200:203], v177 offset:3072
	ds_read_b128 v[204:207], v177 offset:4096
	ds_read_b128 v[212:215], v177 offset:5120
	ds_read_b128 v[216:219], v177 offset:6144
	ds_read_b128 v[220:223], v177 offset:7168
	s_waitcnt lgkmcnt(0)
	v_mfma_f32_16x16x32_bf16 v[30:33], v[224:227], v[188:191], v[30:33]
	v_mfma_f32_16x16x32_bf16 v[26:29], v[232:235], v[188:191], v[26:29]
	v_mfma_f32_16x16x32_bf16 v[22:25], v[224:227], v[196:199], v[22:25]
	v_mfma_f32_16x16x32_bf16 v[14:17], v[232:235], v[196:199], v[14:17]
	v_mfma_f32_16x16x32_bf16 v[10:13], v[224:227], v[204:207], v[10:13]
	v_mfma_f32_16x16x32_bf16 v[6:9], v[232:235], v[204:207], v[6:9]
	v_mfma_f32_16x16x32_bf16 v[2:5], v[224:227], v[216:219], v[2:5]
	v_mfma_f32_16x16x32_bf16 v[18:21], v[232:235], v[216:219], v[18:21]
	v_mfma_f32_16x16x32_bf16 v[30:33], v[228:231], v[192:195], v[30:33]
	v_mfma_f32_16x16x32_bf16 v[26:29], v[236:239], v[192:195], v[26:29]
	v_mfma_f32_16x16x32_bf16 v[22:25], v[228:231], v[200:203], v[22:25]
	v_mfma_f32_16x16x32_bf16 v[14:17], v[236:239], v[200:203], v[14:17]
	v_mfma_f32_16x16x32_bf16 v[10:13], v[228:231], v[212:215], v[10:13]
	v_mfma_f32_16x16x32_bf16 v[6:9], v[236:239], v[212:215], v[6:9]
	v_mfma_f32_16x16x32_bf16 v[2:5], v[228:231], v[220:223], v[2:5]
	v_mfma_f32_16x16x32_bf16 v[18:21], v[236:239], v[220:223], v[18:21]
	s_waitcnt vmcnt(8)
	ds_write_b128 v176, v[60:63] offset:32768
	ds_write_b128 v176, v[64:67] offset:49152
	ds_write_b128 v176, v[68:71] offset:40960
	ds_write_b128 v176, v[72:75] offset:57344
	s_waitcnt lgkmcnt(0)
	s_barrier
	ds_read_b128 v[224:227], v178 offset:32768
	ds_read_b128 v[228:231], v178 offset:33792
	ds_read_b128 v[232:235], v178 offset:34816
	ds_read_b128 v[236:239], v178 offset:35840
	ds_read_b128 v[188:191], v177 offset:32768
	ds_read_b128 v[192:195], v177 offset:33792
	ds_read_b128 v[196:199], v177 offset:34816
	ds_read_b128 v[200:203], v177 offset:35840
	ds_read_b128 v[204:207], v177 offset:36864
	ds_read_b128 v[212:215], v177 offset:37888
	ds_read_b128 v[216:219], v177 offset:38912
	ds_read_b128 v[220:223], v177 offset:39936
	s_waitcnt lgkmcnt(0)
	v_mfma_f32_16x16x32_bf16 v[30:33], v[224:227], v[188:191], v[30:33]
	v_mfma_f32_16x16x32_bf16 v[26:29], v[232:235], v[188:191], v[26:29]
	v_mfma_f32_16x16x32_bf16 v[22:25], v[224:227], v[196:199], v[22:25]
	v_mfma_f32_16x16x32_bf16 v[14:17], v[232:235], v[196:199], v[14:17]
	v_mfma_f32_16x16x32_bf16 v[10:13], v[224:227], v[204:207], v[10:13]
	v_mfma_f32_16x16x32_bf16 v[6:9], v[232:235], v[204:207], v[6:9]
	v_mfma_f32_16x16x32_bf16 v[2:5], v[224:227], v[216:219], v[2:5]
	v_mfma_f32_16x16x32_bf16 v[18:21], v[232:235], v[216:219], v[18:21]
	v_mfma_f32_16x16x32_bf16 v[30:33], v[228:231], v[192:195], v[30:33]
	v_mfma_f32_16x16x32_bf16 v[26:29], v[236:239], v[192:195], v[26:29]
	v_mfma_f32_16x16x32_bf16 v[22:25], v[228:231], v[200:203], v[22:25]
	v_mfma_f32_16x16x32_bf16 v[14:17], v[236:239], v[200:203], v[14:17]
	v_mfma_f32_16x16x32_bf16 v[10:13], v[228:231], v[212:215], v[10:13]
	v_mfma_f32_16x16x32_bf16 v[6:9], v[236:239], v[212:215], v[6:9]
	v_mfma_f32_16x16x32_bf16 v[2:5], v[228:231], v[220:223], v[2:5]
	v_mfma_f32_16x16x32_bf16 v[18:21], v[236:239], v[220:223], v[18:21]
	s_waitcnt vmcnt(4)
	ds_write_b128 v176, v[76:79] offset:0
	ds_write_b128 v176, v[80:83] offset:16384
	ds_write_b128 v176, v[84:87] offset:8192
	ds_write_b128 v176, v[88:91] offset:24576
	s_waitcnt lgkmcnt(0)
	s_barrier
	ds_read_b128 v[224:227], v178 offset:0
	ds_read_b128 v[228:231], v178 offset:1024
	ds_read_b128 v[232:235], v178 offset:2048
	ds_read_b128 v[236:239], v178 offset:3072
	ds_read_b128 v[188:191], v177 offset:0
	ds_read_b128 v[192:195], v177 offset:1024
	ds_read_b128 v[196:199], v177 offset:2048
	ds_read_b128 v[200:203], v177 offset:3072
	ds_read_b128 v[204:207], v177 offset:4096
	ds_read_b128 v[212:215], v177 offset:5120
	ds_read_b128 v[216:219], v177 offset:6144
	ds_read_b128 v[220:223], v177 offset:7168
	s_waitcnt lgkmcnt(0)
	v_mfma_f32_16x16x32_bf16 v[30:33], v[224:227], v[188:191], v[30:33]
	v_mfma_f32_16x16x32_bf16 v[26:29], v[232:235], v[188:191], v[26:29]
	v_mfma_f32_16x16x32_bf16 v[22:25], v[224:227], v[196:199], v[22:25]
	v_mfma_f32_16x16x32_bf16 v[14:17], v[232:235], v[196:199], v[14:17]
	v_mfma_f32_16x16x32_bf16 v[10:13], v[224:227], v[204:207], v[10:13]
	v_mfma_f32_16x16x32_bf16 v[6:9], v[232:235], v[204:207], v[6:9]
	v_mfma_f32_16x16x32_bf16 v[2:5], v[224:227], v[216:219], v[2:5]
	v_mfma_f32_16x16x32_bf16 v[18:21], v[232:235], v[216:219], v[18:21]
	v_mfma_f32_16x16x32_bf16 v[30:33], v[228:231], v[192:195], v[30:33]
	v_mfma_f32_16x16x32_bf16 v[26:29], v[236:239], v[192:195], v[26:29]
	v_mfma_f32_16x16x32_bf16 v[22:25], v[228:231], v[200:203], v[22:25]
	v_mfma_f32_16x16x32_bf16 v[14:17], v[236:239], v[200:203], v[14:17]
	v_mfma_f32_16x16x32_bf16 v[10:13], v[228:231], v[212:215], v[10:13]
	v_mfma_f32_16x16x32_bf16 v[6:9], v[236:239], v[212:215], v[6:9]
	v_mfma_f32_16x16x32_bf16 v[2:5], v[228:231], v[220:223], v[2:5]
	v_mfma_f32_16x16x32_bf16 v[18:21], v[236:239], v[220:223], v[18:21]
	s_waitcnt vmcnt(0)
	ds_write_b128 v176, v[92:95] offset:32768
	ds_write_b128 v176, v[96:99] offset:49152
	ds_write_b128 v176, v[100:103] offset:40960
	ds_write_b128 v176, v[104:107] offset:57344
	s_waitcnt lgkmcnt(0)
	s_barrier
	ds_read_b128 v[224:227], v178 offset:32768
	ds_read_b128 v[228:231], v178 offset:33792
	ds_read_b128 v[232:235], v178 offset:34816
	ds_read_b128 v[236:239], v178 offset:35840
	ds_read_b128 v[188:191], v177 offset:32768
	ds_read_b128 v[192:195], v177 offset:33792
	ds_read_b128 v[196:199], v177 offset:34816
	ds_read_b128 v[200:203], v177 offset:35840
	ds_read_b128 v[204:207], v177 offset:36864
	ds_read_b128 v[212:215], v177 offset:37888
	ds_read_b128 v[216:219], v177 offset:38912
	ds_read_b128 v[220:223], v177 offset:39936
	s_waitcnt lgkmcnt(0)
	v_mfma_f32_16x16x32_bf16 v[30:33], v[224:227], v[188:191], v[30:33]
	v_mfma_f32_16x16x32_bf16 v[26:29], v[232:235], v[188:191], v[26:29]
	v_mfma_f32_16x16x32_bf16 v[22:25], v[224:227], v[196:199], v[22:25]
	v_mfma_f32_16x16x32_bf16 v[14:17], v[232:235], v[196:199], v[14:17]
	v_mfma_f32_16x16x32_bf16 v[10:13], v[224:227], v[204:207], v[10:13]
	v_mfma_f32_16x16x32_bf16 v[6:9], v[232:235], v[204:207], v[6:9]
	v_mfma_f32_16x16x32_bf16 v[2:5], v[224:227], v[216:219], v[2:5]
	v_mfma_f32_16x16x32_bf16 v[18:21], v[232:235], v[216:219], v[18:21]
	v_mfma_f32_16x16x32_bf16 v[30:33], v[228:231], v[192:195], v[30:33]
	v_mfma_f32_16x16x32_bf16 v[26:29], v[236:239], v[192:195], v[26:29]
	v_mfma_f32_16x16x32_bf16 v[22:25], v[228:231], v[200:203], v[22:25]
	v_mfma_f32_16x16x32_bf16 v[14:17], v[236:239], v[200:203], v[14:17]
	v_mfma_f32_16x16x32_bf16 v[10:13], v[228:231], v[212:215], v[10:13]
	v_mfma_f32_16x16x32_bf16 v[6:9], v[236:239], v[212:215], v[6:9]
	v_mfma_f32_16x16x32_bf16 v[2:5], v[228:231], v[220:223], v[2:5]
	v_mfma_f32_16x16x32_bf16 v[18:21], v[236:239], v[220:223], v[18:21]
	s_ashr_i32 s17, s16, 31
	s_lshl_b64 s[16:17], s[16:17], 20
	v_or_b32_e32 v44, s18, v43
	s_add_u32 s16, s42, s16
	s_addc_u32 s17, s43, s17
	v_ashrrev_i32_e32 v45, 31, v44
	v_lshl_add_u64 v[46:47], s[16:17], 0, v[34:35]
	v_lshlrev_b64 v[44:45], 2, v[44:45]
	v_lshl_add_u64 v[46:47], v[46:47], 0, v[44:45]
	s_waitcnt vmcnt(0)
	s_barrier
	global_store_dwordx4 v[46:47], v[30:33], off
	global_store_dwordx4 v[46:47], v[26:29], off offset:64
	s_add_i32 s2, s2, s96
	s_cmpk_lt_i32 s2, 0x80
	v_lshl_add_u64 v[26:27], s[16:17], 0, v[36:37]
	v_lshl_add_u64 v[26:27], v[26:27], 0, v[44:45]
	global_store_dwordx4 v[26:27], v[22:25], off
	global_store_dwordx4 v[26:27], v[14:17], off offset:64
	s_nop 1
	v_lshl_add_u64 v[14:15], s[16:17], 0, v[38:39]
	v_lshl_add_u64 v[14:15], v[14:15], 0, v[44:45]
	global_store_dwordx4 v[14:15], v[10:13], off
	global_store_dwordx4 v[14:15], v[6:9], off offset:64
	s_nop 1
	v_lshl_add_u64 v[6:7], s[16:17], 0, v[40:41]
	v_lshl_add_u64 v[6:7], v[6:7], 0, v[44:45]
	global_store_dwordx4 v[6:7], v[2:5], off
	global_store_dwordx4 v[6:7], v[18:21], off offset:64
	s_cbranch_scc1 .LBB0_950
